# scan phase start: per-XCD jitter (bid&7) x 0.27 us so the scan steps of different workgroups are not issued in phase
# speedup vs baseline: 1.0073x; 1.0052x over previous
.Lj7_loop:
	s_sleep 10
	s_sub_u32 s8, s8, 1
	s_cmp_lg_u32 s8, 0
	s_cbranch_scc1 .Lj7_loop
.Lj7_skip:
	v_readlane_b32 s0, v253, 0
	v_lshrrev_b32_e32 v0, 8, v0
	v_mul_u32_u24_e32 v122, 0x12000, v0
	v_mov_b32_e32 v0, v154
	s_nop 0
	v_writelane_b32 v254, s0, 62
	v_readfirstlane_b32 s1, v0
	s_lshl_b32 s0, s0, 1
	v_writelane_b32 v255, s0, 0
	v_writelane_b32 v254, s1, 63
	s_ashr_i32 s1, s1, 8
	s_add_i32 s0, s1, s0
	v_writelane_b32 v255, s1, 1
	v_writelane_b32 v254, s0, 61
	s_cmpk_gt_i32 s0, 0xff
	s_mov_b64 s[0:1], -1
	s_cbranch_scc0 .LBB0_465
	v_readlane_b32 s0, v254, 61
	s_cmpk_gt_u32 s0, 0x4ff
	s_cbranch_scc1 .LBB0_430
	v_readlane_b32 s0, v254, 61
	s_add_i32 s23, s0, 0xffffff00
	v_readlane_b32 s0, v254, 57
	s_lshl_b32 s12, s0, 6
	s_branch .LBB0_396
